# P0 segment deferral guarded by the 256-workgroup grid check
# speedup vs baseline: 1.0067x; 1.0026x over previous
; #define SEG(cnt, ...) if (r < (cnt)) { p0_transpose_item(__VA_ARGS__); continue; } r -= (cnt);
; __global__ void __launch_bounds__(NTHREADS, 2) hybrid_fwd(Params P) {
;     ...
;         for (int it = gw; it < NITEMS; it += NGW) {
;             int r = it;
;     ...
;             SEG(5376, w_in_even, 2048, EIN, WinE, 0, scr, r, lane, norm_mix, 0, 0, 1.f)
;             SEG(5376, w_in_even + (size_t)2048 * EIN, 2048, EIN, WinE + (size_t)EIN * 2048, 0, scr, r, lane, norm_mix + 2 * 2048, 0, 0, 1.f)
;             SEG(2048, w_out_even, 2048, 2048, WoutE, 0, scr, r, lane, nullptr, 0, 0, 1.f)
;             SEG(2048, w_out_even + (size_t)2048 * 2048, 2048, 2048, WoutE + (size_t)2048 * 2048, 0, scr, r, lane, nullptr, 0, 0, 1.f)
;             SEG(12288, w_in_ret, 2048, RIN, WinR, 0, scr, r, lane, norm_mix + 1 * 2048, 2048, 4096, 0.0625f)
;             SEG(12288, w_in_ret + (size_t)2048 * RIN, 2048, RIN, WinR + (size_t)RIN * 2048, 0, scr, r, lane, norm_mix + 3 * 2048, 2048, 4096, 0.0625f)
;             SEG(4096, w_out_ret, 4096, 2048, WoutR, 0, scr, r, lane, nullptr, 0, 0, 1.f)
;             SEG(4096, w_out_ret + (size_t)4096 * 2048, 4096, 2048, WoutR + (size_t)2048 * 4096, 0, scr, r, lane, nullptr, 0, 0, 1.f)
;             {
;                 const int l = r >> 11, q = (r >> 9) & 3, rr = r & 511;
;                 if (q == 0) p0_transpose_item(w_xq + (size_t)l * 2048 * 512, 2048, 512, Wxq + (size_t)l * 512 * 2048, 0, scr, rr, lane, norm_cross + l * 2048, 0, 0, 1.f);
;                 else if (q == 1) p0_transpose_item(w_xo + (size_t)l * 512 * 2048, 512, 2048, Wxo + (size_t)l * 2048 * 512, 0, scr, rr, lane, nullptr, 0, 0, 1.f);
;                 else if (q == 2) p0_transpose_item(w_xk + (size_t)l * 2048 * 512, 2048, 512, Wxkv, l * 1024, scr, rr, lane, norm_mem + l * 2048, 0, 0, 1.f);
;                 else p0_transpose_item(w_xv + (size_t)l * 2048 * 512, 2048, 512, Wxkv, l * 1024 + 512, scr, rr, lane, norm_mem + l * 2048, 0, 0, 1.f);
;             }
;     ...
;         }
.Lp0g_0:
	s_cmpk_eq_i32 s88, 0x100
	s_cbranch_scc1 .LBB0_23
	s_branch .LBB0_98
